# barrier variant with two grouped LDS waits per scan pair and the fold block's LDS writes spread between its FMAs
# speedup vs baseline: 1.0168x; 1.0025x over previous
.LBB0_659:
	s_or_b64 exec, exec, s[10:11]
	s_or_b32 s22, s4, 32
	s_mov_b32 s23, s5
	v_lshl_add_u64 v[6:7], s[22:23], 0, v[26:27]
	v_lshlrev_b64 v[6:7], 11, v[6:7]
	v_lshlrev_b32_e32 v25, 1, v55
	v_or_b32_e32 v6, v6, v25
	v_lshl_add_u64 v[8:9], s[70:71], 0, v[6:7]
	v_lshl_add_u64 v[10:11], s[12:13], 0, v[6:7]
	v_lshl_add_u64 v[12:13], s[14:15], 0, v[6:7]
	v_lshl_add_u64 v[14:15], s[16:17], 0, v[6:7]
	v_lshl_add_u64 v[16:17], s[18:19], 0, v[6:7]
	v_or_b32_e32 v6, 0x800, v6
	global_load_dwordx2 v[10:11], v[10:11], off
	v_lshl_add_u64 v[18:19], s[12:13], 0, v[6:7]
	global_load_dwordx2 v[14:15], v[14:15], off
	s_nop 0
	global_load_dwordx2 v[18:19], v[18:19], off
	s_nop 0
	global_load_dwordx2 v[20:21], v[8:9], off
	global_load_dwordx2 v[56:57], v[12:13], off
	s_nop 0
	global_load_dwordx2 v[12:13], v[8:9], off offset:2048
	v_lshl_add_u64 v[8:9], s[16:17], 0, v[6:7]
	global_load_dwordx2 v[64:65], v[8:9], off
	global_load_dwordx2 v[68:69], v[16:17], off
	v_cvt_f32_f16_sdwa v9, v3 dst_sel:DWORD dst_unused:UNUSED_PAD src0_sel:WORD_1
	v_cvt_f32_f16_e32 v8, v3
	s_or_b32 s26, s4, 64
	s_mov_b32 s27, s5
	v_lshl_add_u64 v[34:35], s[22:23], 0, v[4:5]
	v_lshl_add_u64 v[36:37], s[26:27], 0, v[26:27]
	v_lshlrev_b32_e32 v1, 6, v4
	s_mov_b32 s11, 0
	v_lshlrev_b32_e32 v24, 2, v58
	v_lshl_add_u64 v[38:39], s[26:27], 0, v[4:5]
	v_lshlrev_b64 v[34:35], 11, v[34:35]
	v_lshlrev_b64 v[36:37], 11, v[36:37]
	v_add3_u32 v1, 0, v1, v24
	s_mov_b32 s7, s11
	v_lshlrev_b64 v[38:39], 11, v[38:39]
	v_lshl_add_u64 v[34:35], s[20:21], 0, v[34:35]
	v_or_b32_e32 v36, v36, v25
	v_lshl_add_u64 v[38:39], s[20:21], 0, v[38:39]
	ds_write_b64 v1, v[8:9] offset:37632
	ds_read_b128 v[198:201], v216 offset:36864
	ds_read_b128 v[202:205], v216 offset:36880
	ds_read2_b32 v[206:207], v220 offset1:16
	s_waitcnt lgkmcnt(0)
	v_mul_f32_e32 v210, 0x41800000, v200
	v_mul_f32_e32 v211, 0x41800000, v202
	v_mul_f32_e32 v212, 0x41800000, v204
	v_fma_f32 v213, -v204, v199, v203
	v_fma_f32 v121, -v198, v120, v121
	v_fma_f32 v123, -v198, v122, v123
	ds_write_b128 v218, v[120:123]
	v_fma_f32 v124, -v210, v120, v124
	v_fma_f32 v125, -v211, v120, v125
	v_fma_f32 v125, -v212, v121, v125
	v_fma_f32 v126, -v210, v122, v126
	v_fma_f32 v127, -v211, v122, v127
	v_fma_f32 v127, -v212, v123, v127
	ds_write_b128 v218, v[124:127] offset:256
	v_fma_f32 v129, -v198, v128, v129
	v_fma_f32 v131, -v198, v130, v131
	ds_write_b128 v218, v[128:131] offset:512
	v_fma_f32 v132, -v210, v128, v132
	v_fma_f32 v133, -v211, v128, v133
	v_fma_f32 v133, -v212, v129, v133
	v_fma_f32 v134, -v210, v130, v134
	v_fma_f32 v135, -v211, v130, v135
	v_fma_f32 v135, -v212, v131, v135
	ds_write_b128 v218, v[132:135] offset:768
	v_fma_f32 v182, -v199, v186, v182
	v_fma_f32 v183, -v199, v187, v183
	v_fma_f32 v184, -v199, v188, v184
	v_fma_f32 v185, -v199, v189, v185
	ds_write_b128 v218, v[182:185] offset:1280
	v_mul_f32_e32 v208, v206, v201
	v_mul_f32_e32 v209, v206, v213
	v_fmac_f32_e32 v209, v207, v205
	ds_write_b128 v222, v[206:209]
	v_lshl_add_u64 v[8:9], v[34:35], 0, s[6:7]
	v_lshl_add_u64 v[34:35], s[14:15], 0, v[36:37]
	v_lshl_add_u64 v[40:41], s[16:17], 0, v[36:37]
	v_lshl_add_u64 v[50:51], s[14:15], 0, v[6:7]
	v_lshl_add_u64 v[46:47], s[18:19], 0, v[36:37]
	v_lshl_add_u64 v[48:49], v[38:39], 0, s[6:7]
	v_lshl_add_u64 v[6:7], s[18:19], 0, v[6:7]
	global_load_dwordx2 v[38:39], v[34:35], off
	global_load_dwordx2 v[42:43], v[40:41], off
	s_nop 0
	global_load_dwordx2 v[40:41], v[46:47], off
	global_load_dwordx2 v[70:71], v[50:51], off
	global_load_dwordx2 v[72:73], v[6:7], off
	s_add_i32 s10, 0, 0x11b00
	s_mov_b32 s9, s11
	v_lshl_add_u64 v[16:17], s[70:71], 0, v[36:37]
	v_lshl_add_u64 v[44:45], s[12:13], 0, v[36:37]
	v_or_b32_e32 v36, 0x800, v36
	v_mov_b32_e32 v3, 0
	v_lshl_add_u32 v22, v22, 2, s10
	v_lshl_add_u64 v[8:9], v[8:9], 0, s[8:9]
	v_lshl_add_u64 v[34:35], s[12:13], 0, v[36:37]
	v_lshl_add_u64 v[46:47], s[14:15], 0, v[36:37]
	v_lshl_add_u64 v[66:67], s[16:17], 0, v[36:37]
	v_lshl_add_u64 v[36:37], s[18:19], 0, v[36:37]
	v_lshl_add_u64 v[48:49], v[48:49], 0, s[8:9]
	v_add_u32_e32 v76, v22, v62
	v_lshl_add_u64 v[6:7], v[8:9], 0, v[2:3]
	global_load_dwordx2 v[52:53], v[34:35], off
	s_nop 0
	global_load_dwordx2 v[34:35], v[46:47], off
	s_nop 0
	global_load_dwordx2 v[46:47], v[66:67], off
	s_nop 0
	global_load_dwordx2 v[36:37], v[36:37], off
	v_lshl_add_u64 v[8:9], v[48:49], 0, v[2:3]
	global_load_dwordx2 v[50:51], v[44:45], off
	global_load_dword v22, v[6:7], off
	global_load_dwordx2 v[48:49], v[16:17], off
	s_nop 0
	global_load_dwordx2 v[44:45], v[16:17], off offset:2048
	global_load_dword v61, v[8:9], off
	s_waitcnt lgkmcnt(0)
	s_barrier
	v_lshlrev_b32_e32 v60, 4, v4
	v_add_u32_e32 v77, 0, v23
	s_waitcnt vmcnt(19)
	v_cvt_f32_f16_e32 v16, v18
	v_cvt_f32_f16_sdwa v17, v18 dst_sel:DWORD dst_unused:UNUSED_PAD src0_sel:WORD_1
	v_cvt_f32_f16_e32 v8, v10
	v_cvt_f32_f16_sdwa v9, v10 dst_sel:DWORD dst_unused:UNUSED_PAD src0_sel:WORD_1
	v_cvt_f32_f16_e32 v10, v11
	v_pk_add_f32 v[78:79], v[16:17], 1.0 op_sel_hi:[1,0] neg_lo:[1,0] neg_hi:[1,0]
	v_cvt_f32_f16_e32 v16, v19
	v_cvt_f32_f16_sdwa v17, v19 dst_sel:DWORD dst_unused:UNUSED_PAD src0_sel:WORD_1
	v_cvt_f32_f16_sdwa v11, v11 dst_sel:DWORD dst_unused:UNUSED_PAD src0_sel:WORD_1
	s_waitcnt vmcnt(16)
	v_cvt_f32_f16_e32 v80, v12
	v_cvt_f32_f16_sdwa v81, v12 dst_sel:DWORD dst_unused:UNUSED_PAD src0_sel:WORD_1
	s_waitcnt vmcnt(15)
	v_cvt_f32_f16_e32 v82, v64
	v_cvt_f32_f16_sdwa v83, v64 dst_sel:DWORD dst_unused:UNUSED_PAD src0_sel:WORD_1
	v_cvt_f32_f16_e32 v92, v65
	v_cvt_f32_f16_sdwa v93, v65 dst_sel:DWORD dst_unused:UNUSED_PAD src0_sel:WORD_1
	v_cvt_f32_f16_e32 v94, v13
	v_cvt_f32_f16_sdwa v95, v13 dst_sel:DWORD dst_unused:UNUSED_PAD src0_sel:WORD_1
	v_cvt_f32_f16_e32 v6, v14
	v_cvt_f32_f16_sdwa v7, v14 dst_sel:DWORD dst_unused:UNUSED_PAD src0_sel:WORD_1
	v_cvt_f32_f16_e32 v74, v20
	v_pk_add_f32 v[66:67], v[8:9], 1.0 op_sel_hi:[1,0] neg_lo:[1,0] neg_hi:[1,0]
	v_cvt_f32_f16_sdwa v75, v20 dst_sel:DWORD dst_unused:UNUSED_PAD src0_sel:WORD_1
	v_cvt_f32_f16_e32 v8, v15
	v_cvt_f32_f16_sdwa v9, v15 dst_sel:DWORD dst_unused:UNUSED_PAD src0_sel:WORD_1
	v_cvt_f32_f16_e32 v90, v21
	v_cvt_f32_f16_sdwa v91, v21 dst_sel:DWORD dst_unused:UNUSED_PAD src0_sel:WORD_1
	v_pk_add_f32 v[86:87], v[16:17], 1.0 op_sel_hi:[1,0] neg_lo:[1,0] neg_hi:[1,0]
	v_pk_add_f32 v[88:89], v[10:11], 1.0 op_sel_hi:[1,0] neg_lo:[1,0] neg_hi:[1,0]
	v_pk_mul_f32 v[84:85], v[78:79], v[80:81]
	v_pk_mul_f32 v[14:15], v[66:67], v[82:83]
	v_pk_mul_f32 v[16:17], v[88:89], v[92:93]
	v_pk_mul_f32 v[96:97], v[86:87], v[94:95]
	v_pk_mul_f32 v[10:11], v[66:67], v[74:75]
	v_pk_mul_f32 v[12:13], v[88:89], v[90:91]
	v_pk_mul_f32 v[18:19], v[66:67], v[84:85]
	v_pk_mul_f32 v[20:21], v[88:89], v[96:97]
	v_pk_mul_f32 v[64:65], v[66:67], v[78:79]
	v_pk_mul_f32 v[66:67], v[88:89], v[86:87]
	v_mov_b32_e32 v120, v6
	v_mov_b32_e32 v121, v14
	v_mov_b32_e32 v122, v7
	v_mov_b32_e32 v123, v15
	v_mov_b32_e32 v124, v10
	v_mov_b32_e32 v125, v18
	v_mov_b32_e32 v126, v11
	v_mov_b32_e32 v127, v19
	v_mov_b32_e32 v128, v8
	v_mov_b32_e32 v129, v16
	v_mov_b32_e32 v130, v9
	v_mov_b32_e32 v131, v17
	v_mov_b32_e32 v132, v12
	v_mov_b32_e32 v133, v20
	v_mov_b32_e32 v134, v13
	v_mov_b32_e32 v135, v21
	ds_write_b128 v76, v[64:67] offset:1024
	s_waitcnt vmcnt(14)
	v_cvt_f32_f16_e32 v14, v68
	v_cvt_f32_f16_sdwa v16, v68 dst_sel:DWORD dst_unused:UNUSED_PAD src0_sel:WORD_1
	v_cvt_f32_f16_e32 v15, v56
	v_cvt_f32_f16_sdwa v17, v56 dst_sel:DWORD dst_unused:UNUSED_PAD src0_sel:WORD_1
	v_cvt_f32_f16_e32 v21, v57
	v_cvt_f32_f16_sdwa v57, v57 dst_sel:DWORD dst_unused:UNUSED_PAD src0_sel:WORD_1
	v_cvt_f32_f16_e32 v20, v69
	v_cvt_f32_f16_sdwa v56, v69 dst_sel:DWORD dst_unused:UNUSED_PAD src0_sel:WORD_1
	v_mov_b32_e32 v8, v14
	v_mov_b32_e32 v9, v16
	v_mov_b32_e32 v6, v15
	v_mov_b32_e32 v7, v17
	v_pk_mul_f32 v[10:11], v[78:79], v[8:9]
	v_mov_b32_e32 v8, v21
	v_mov_b32_e32 v9, v57
	v_pk_mul_f32 v[6:7], v[78:79], v[6:7]
	v_pk_mul_f32 v[8:9], v[86:87], v[8:9]
	v_mov_b32_e32 v12, v20
	v_mov_b32_e32 v13, v56
	v_mov_b32_e32 v18, v83
	v_pk_mul_f32 v[12:13], v[86:87], v[12:13]
	v_mov_b32_e32 v182, v6
	v_mov_b32_e32 v183, v7
	v_mov_b32_e32 v184, v8
	v_mov_b32_e32 v185, v9
	ds_write_b128 v76, v[10:13] offset:1536
	v_pk_fma_f32 v[6:7], v[82:83], v[14:15], 0 op_sel_hi:[0,1,0]
	v_pk_fma_f32 v[6:7], v[18:19], v[16:17], v[6:7] op_sel_hi:[0,1,1]
	v_mov_b32_e32 v10, v75
	v_pk_fma_f32 v[18:19], v[74:75], v[14:15], 0 op_sel_hi:[0,1,0]
	v_pk_fma_f32 v[14:15], v[84:85], v[14:15], 0 op_sel_hi:[0,1,0]
	v_pk_fma_f32 v[10:11], v[10:11], v[16:17], v[18:19] op_sel_hi:[0,1,1]
	v_pk_fma_f32 v[14:15], v[84:85], v[16:17], v[14:15] op_sel:[1,0,0]
	v_mov_b32_e32 v54, v93
	v_pk_fma_f32 v[6:7], v[92:93], v[20:21], v[6:7] op_sel_hi:[0,1,1]
	v_mov_b32_e32 v12, v91
	v_pk_fma_f32 v[10:11], v[90:91], v[20:21], v[10:11] op_sel_hi:[0,1,1]
	v_pk_fma_f32 v[14:15], v[96:97], v[20:21], v[14:15] op_sel_hi:[0,1,1]
	v_pk_fma_f32 v[6:7], v[54:55], v[56:57], v[6:7] op_sel_hi:[0,1,1]
	v_pk_fma_f32 v[10:11], v[12:13], v[56:57], v[10:11] op_sel_hi:[0,1,1]
	v_pk_fma_f32 v[14:15], v[96:97], v[56:57], v[14:15] op_sel:[1,0,0]
	s_waitcnt vmcnt(10)
	v_cvt_f32_f16_e32 v57, v70
	v_cvt_f32_f16_sdwa v65, v70 dst_sel:DWORD dst_unused:UNUSED_PAD src0_sel:WORD_1
	v_cvt_f32_f16_e32 v67, v71
	v_cvt_f32_f16_sdwa v69, v71 dst_sel:DWORD dst_unused:UNUSED_PAD src0_sel:WORD_1
	s_waitcnt vmcnt(9)
	v_cvt_f32_f16_e32 v56, v72
	v_cvt_f32_f16_sdwa v64, v72 dst_sel:DWORD dst_unused:UNUSED_PAD src0_sel:WORD_1
	v_cvt_f32_f16_e32 v66, v73
	v_cvt_f32_f16_sdwa v68, v73 dst_sel:DWORD dst_unused:UNUSED_PAD src0_sel:WORD_1
	v_mov_b32_e32 v18, v57
	v_mov_b32_e32 v19, v65
	v_mov_b32_e32 v20, v67
	v_mov_b32_e32 v21, v69
	ds_write_b128 v76, v[18:21] offset:1792
	v_mov_b32_e32 v18, v56
	v_mov_b32_e32 v19, v64
	v_mov_b32_e32 v20, v66
	v_mov_b32_e32 v21, v68
	v_mov_b32_e32 v54, v81
	ds_write_b128 v76, v[18:21] offset:2048
	v_mov_b32_e32 v186, v18
	v_mov_b32_e32 v187, v19
	v_mov_b32_e32 v188, v20
	v_mov_b32_e32 v189, v21
	v_pk_fma_f32 v[18:19], v[80:81], v[56:57], 0 op_sel_hi:[0,1,0]
	v_pk_fma_f32 v[18:19], v[54:55], v[64:65], v[18:19] op_sel_hi:[0,1,1]
	v_mov_b32_e32 v70, v95
	v_pk_fma_f32 v[18:19], v[94:95], v[66:67], v[18:19] op_sel_hi:[0,1,1]
	v_pk_fma_f32 v[18:19], v[70:71], v[68:69], v[18:19] op_sel_hi:[0,1,1]
	v_mov_b32_dpp v8, v6 row_ror:8 row_mask:0xf bank_mask:0xf bound_ctrl:1
	v_mov_b32_dpp v9, v7 row_ror:8 row_mask:0xf bank_mask:0xf bound_ctrl:1
	v_mov_b32_dpp v12, v10 row_ror:8 row_mask:0xf bank_mask:0xf bound_ctrl:1
	v_mov_b32_dpp v13, v11 row_ror:8 row_mask:0xf bank_mask:0xf bound_ctrl:1
	v_mov_b32_dpp v16, v14 row_ror:8 row_mask:0xf bank_mask:0xf bound_ctrl:1
	v_mov_b32_dpp v17, v15 row_ror:8 row_mask:0xf bank_mask:0xf bound_ctrl:1
	v_mov_b32_dpp v20, v18 row_ror:8 row_mask:0xf bank_mask:0xf bound_ctrl:1
	v_mov_b32_dpp v21, v19 row_ror:8 row_mask:0xf bank_mask:0xf bound_ctrl:1
	v_pk_add_f32 v[6:7], v[6:7], v[8:9]
	v_pk_add_f32 v[10:11], v[10:11], v[12:13]
	v_pk_add_f32 v[14:15], v[14:15], v[16:17]
	v_pk_add_f32 v[18:19], v[18:19], v[20:21]
	v_mov_b32_dpp v8, v6 row_ror:4 row_mask:0xf bank_mask:0xf bound_ctrl:1
	v_mov_b32_dpp v9, v7 row_ror:4 row_mask:0xf bank_mask:0xf bound_ctrl:1
	v_mov_b32_dpp v12, v10 row_ror:4 row_mask:0xf bank_mask:0xf bound_ctrl:1
	v_mov_b32_dpp v13, v11 row_ror:4 row_mask:0xf bank_mask:0xf bound_ctrl:1
	v_mov_b32_dpp v16, v14 row_ror:4 row_mask:0xf bank_mask:0xf bound_ctrl:1
	v_mov_b32_dpp v17, v15 row_ror:4 row_mask:0xf bank_mask:0xf bound_ctrl:1
	v_mov_b32_dpp v20, v18 row_ror:4 row_mask:0xf bank_mask:0xf bound_ctrl:1
	v_mov_b32_dpp v21, v19 row_ror:4 row_mask:0xf bank_mask:0xf bound_ctrl:1
	v_pk_add_f32 v[6:7], v[6:7], v[8:9]
	v_pk_add_f32 v[10:11], v[10:11], v[12:13]
	v_pk_add_f32 v[14:15], v[14:15], v[16:17]
	v_pk_add_f32 v[18:19], v[18:19], v[20:21]
	v_mov_b32_dpp v8, v6 row_ror:2 row_mask:0xf bank_mask:0xf bound_ctrl:1
	v_mov_b32_dpp v9, v7 row_ror:2 row_mask:0xf bank_mask:0xf bound_ctrl:1
	v_mov_b32_dpp v12, v10 row_ror:2 row_mask:0xf bank_mask:0xf bound_ctrl:1
	v_mov_b32_dpp v13, v11 row_ror:2 row_mask:0xf bank_mask:0xf bound_ctrl:1
	v_mov_b32_dpp v16, v14 row_ror:2 row_mask:0xf bank_mask:0xf bound_ctrl:1
	v_mov_b32_dpp v17, v15 row_ror:2 row_mask:0xf bank_mask:0xf bound_ctrl:1
	v_mov_b32_dpp v20, v18 row_ror:2 row_mask:0xf bank_mask:0xf bound_ctrl:1
	v_mov_b32_dpp v21, v19 row_ror:2 row_mask:0xf bank_mask:0xf bound_ctrl:1
	v_pk_add_f32 v[6:7], v[6:7], v[8:9]
	v_pk_add_f32 v[10:11], v[10:11], v[12:13]
	v_pk_add_f32 v[14:15], v[14:15], v[16:17]
	v_pk_add_f32 v[18:19], v[18:19], v[20:21]
	v_mov_b32_dpp v8, v6 row_ror:1 row_mask:0xf bank_mask:0xf bound_ctrl:1
	v_mov_b32_dpp v9, v7 row_ror:1 row_mask:0xf bank_mask:0xf bound_ctrl:1
	v_mov_b32_dpp v12, v10 row_ror:1 row_mask:0xf bank_mask:0xf bound_ctrl:1
	v_mov_b32_dpp v13, v11 row_ror:1 row_mask:0xf bank_mask:0xf bound_ctrl:1
	v_mov_b32_dpp v16, v14 row_ror:1 row_mask:0xf bank_mask:0xf bound_ctrl:1
	v_mov_b32_dpp v17, v15 row_ror:1 row_mask:0xf bank_mask:0xf bound_ctrl:1
	v_mov_b32_dpp v20, v18 row_ror:1 row_mask:0xf bank_mask:0xf bound_ctrl:1
	v_mov_b32_dpp v21, v19 row_ror:1 row_mask:0xf bank_mask:0xf bound_ctrl:1
	s_and_saveexec_b64 s[22:23], s[0:1]
	s_cbranch_execz .LBB0_661
	v_pk_add_f32 v[6:7], v[6:7], v[8:9]
	v_pk_add_f32 v[8:9], v[10:11], v[12:13]
	s_mov_b32 s10, 0x3d800000
	v_pk_mul_f32 v[8:9], v[8:9], s[10:11] op_sel_hi:[1,0]
	v_add_u32_e32 v10, 0x1ab00, v77
	ds_write_b128 v10, v[6:9]
	v_pk_add_f32 v[6:7], v[14:15], v[16:17]
	v_pk_add_f32 v[8:9], v[18:19], v[20:21]
	v_pk_mul_f32 v[6:7], v[6:7], s[10:11] op_sel_hi:[1,0]
	v_pk_mul_f32 v[8:9], v[8:9], s[10:11] op_sel_hi:[1,0]
	ds_write_b128 v10, v[6:9] offset:16
.LBB0_661:
	s_or_b64 exec, exec, s[22:23]
	v_lshlrev_b32_e32 v6, 2, v60
	s_add_i32 s7, 0, 0x1ae00
	v_add3_u32 v78, s7, v6, v24
	s_add_u32 s7, s20, s6
	s_addc_u32 s9, s21, 0
	s_add_u32 s20, s7, s8
	s_waitcnt vmcnt(3)
	v_cvt_f32_f16_sdwa v7, v22 dst_sel:DWORD dst_unused:UNUSED_PAD src0_sel:WORD_1
	v_cvt_f32_f16_e32 v6, v22
	s_addc_u32 s21, s9, 0
	v_lshl_add_u64 v[56:57], s[20:21], 0, v[2:3]
	s_mov_b64 s[20:21], 0x18000
	v_or_b32_e32 v54, 0x400, v55
	v_lshl_add_u64 v[16:17], v[28:29], 0, s[20:21]
	ds_write_b64 v78, v[6:7]
	ds_read_b128 v[198:201], v217 offset:36864
	ds_read_b128 v[202:205], v217 offset:36880
	ds_read2_b32 v[206:207], v221 offset1:16
	s_waitcnt lgkmcnt(0)
	v_mul_f32_e32 v210, 0x41800000, v200
	v_mul_f32_e32 v211, 0x41800000, v202
	v_mul_f32_e32 v212, 0x41800000, v204
	v_fma_f32 v213, -v204, v199, v203
	v_fma_f32 v121, -v198, v120, v121
	v_fma_f32 v123, -v198, v122, v123
	ds_write_b128 v219, v[120:123]
	v_fma_f32 v124, -v210, v120, v124
	v_fma_f32 v125, -v211, v120, v125
	v_fma_f32 v125, -v212, v121, v125
	v_fma_f32 v126, -v210, v122, v126
	v_fma_f32 v127, -v211, v122, v127
	v_fma_f32 v127, -v212, v123, v127
	ds_write_b128 v219, v[124:127] offset:256
	v_fma_f32 v129, -v198, v128, v129
	v_fma_f32 v131, -v198, v130, v131
	ds_write_b128 v219, v[128:131] offset:512
	v_fma_f32 v132, -v210, v128, v132
	v_fma_f32 v133, -v211, v128, v133
	v_fma_f32 v133, -v212, v129, v133
	v_fma_f32 v134, -v210, v130, v134
	v_fma_f32 v135, -v211, v130, v135
	v_fma_f32 v135, -v212, v131, v135
	ds_write_b128 v219, v[132:135] offset:768
	v_fma_f32 v182, -v199, v186, v182
	v_fma_f32 v183, -v199, v187, v183
	v_fma_f32 v184, -v199, v188, v184
	v_fma_f32 v185, -v199, v189, v185
	ds_write_b128 v219, v[182:185] offset:1280
	v_mul_f32_e32 v208, v206, v201
	v_mul_f32_e32 v209, v206, v213
	v_fmac_f32_e32 v209, v207, v205
	ds_write_b128 v223, v[206:209]
	v_or_b32_e32 v6, v16, v55
	v_mov_b32_e32 v7, v17
	v_or_b32_e32 v16, v16, v54
	v_lshlrev_b64 v[12:13], 1, v[6:7]
	v_lshlrev_b64 v[22:23], 1, v[16:17]
	v_lshl_add_u64 v[56:57], v[56:57], 0, v[32:33]
	s_mov_b32 s7, 0x30000
	v_lshl_add_u64 v[6:7], s[70:71], 0, v[12:13]
	v_lshl_add_u64 v[8:9], s[12:13], 0, v[12:13]
	v_lshl_add_u64 v[10:11], s[14:15], 0, v[12:13]
	v_lshl_add_u64 v[14:15], s[16:17], 0, v[12:13]
	v_lshl_add_u64 v[18:19], s[18:19], 0, v[12:13]
	v_lshl_add_u64 v[16:17], s[70:71], 0, v[22:23]
	v_lshl_add_u64 v[20:21], s[12:13], 0, v[22:23]
	v_lshl_add_u64 v[24:25], s[14:15], 0, v[22:23]
	v_add_co_u32_e32 v32, vcc, s7, v56
	global_load_dwordx2 v[6:7], v[6:7], off
	s_nop 0
	global_load_dwordx2 v[8:9], v[8:9], off
	s_nop 0
	global_load_dwordx2 v[10:11], v[10:11], off
	s_nop 0
	global_load_dwordx2 v[12:13], v[14:15], off
	s_nop 0
	global_load_dwordx2 v[14:15], v[18:19], off
	s_nop 0
	global_load_dwordx2 v[18:19], v[16:17], off
	s_nop 0
	global_load_dwordx2 v[16:17], v[20:21], off
	s_nop 0
	global_load_dwordx2 v[20:21], v[24:25], off
	v_lshl_add_u64 v[24:25], s[16:17], 0, v[22:23]
	v_lshl_add_u64 v[22:23], s[18:19], 0, v[22:23]
	v_addc_co_u32_e32 v33, vcc, 0, v57, vcc
	global_load_dwordx2 v[24:25], v[24:25], off
	s_nop 0
	global_load_dwordx2 v[22:23], v[22:23], off
	v_cvt_f32_f16_sdwa v67, v50 dst_sel:DWORD dst_unused:UNUSED_PAD src0_sel:WORD_1
	global_load_dword v79, v[32:33], off
	v_cvt_f32_f16_e32 v66, v50
	v_cvt_f32_f16_sdwa v33, v52 dst_sel:DWORD dst_unused:UNUSED_PAD src0_sel:WORD_1
	v_cvt_f32_f16_e32 v32, v52
	v_cvt_f32_f16_sdwa v71, v53 dst_sel:DWORD dst_unused:UNUSED_PAD src0_sel:WORD_1
	v_cvt_f32_f16_e32 v70, v53
	s_waitcnt vmcnt(12)
	v_cvt_f32_f16_sdwa v75, v44 dst_sel:DWORD dst_unused:UNUSED_PAD src0_sel:WORD_1
	v_cvt_f32_f16_e32 v74, v44
	v_cvt_f32_f16_sdwa v53, v51 dst_sel:DWORD dst_unused:UNUSED_PAD src0_sel:WORD_1
	v_cvt_f32_f16_e32 v52, v51
	v_cvt_f32_f16_sdwa v93, v45 dst_sel:DWORD dst_unused:UNUSED_PAD src0_sel:WORD_1
	v_cvt_f32_f16_e32 v92, v45
	v_cvt_f32_f16_sdwa v65, v42 dst_sel:DWORD dst_unused:UNUSED_PAD src0_sel:WORD_1
	v_cvt_f32_f16_e32 v64, v42
	v_pk_add_f32 v[68:69], v[66:67], 1.0 op_sel_hi:[1,0] neg_lo:[1,0] neg_hi:[1,0]
	v_cvt_f32_f16_sdwa v73, v48 dst_sel:DWORD dst_unused:UNUSED_PAD src0_sel:WORD_1
	v_cvt_f32_f16_e32 v72, v48
	v_cvt_f32_f16_sdwa v83, v46 dst_sel:DWORD dst_unused:UNUSED_PAD src0_sel:WORD_1
	v_cvt_f32_f16_e32 v82, v46
	v_cvt_f32_f16_sdwa v67, v43 dst_sel:DWORD dst_unused:UNUSED_PAD src0_sel:WORD_1
	v_cvt_f32_f16_e32 v66, v43
	v_cvt_f32_f16_sdwa v89, v49 dst_sel:DWORD dst_unused:UNUSED_PAD src0_sel:WORD_1
	v_cvt_f32_f16_e32 v88, v49
	v_cvt_f32_f16_sdwa v91, v47 dst_sel:DWORD dst_unused:UNUSED_PAD src0_sel:WORD_1
	v_cvt_f32_f16_e32 v90, v47
	v_pk_add_f32 v[32:33], v[32:33], 1.0 op_sel_hi:[1,0] neg_lo:[1,0] neg_hi:[1,0]
	v_pk_add_f32 v[86:87], v[70:71], 1.0 op_sel_hi:[1,0] neg_lo:[1,0] neg_hi:[1,0]
	v_pk_mul_f32 v[84:85], v[32:33], v[74:75]
	v_pk_add_f32 v[70:71], v[52:53], 1.0 op_sel_hi:[1,0] neg_lo:[1,0] neg_hi:[1,0]
	v_pk_mul_f32 v[94:95], v[86:87], v[92:93]
	v_pk_mul_f32 v[50:51], v[68:69], v[84:85]
	v_pk_mul_f32 v[52:53], v[70:71], v[94:95]
	v_add_u32_e32 v80, v59, v62
	s_waitcnt lgkmcnt(0)
	s_barrier
	v_pk_mul_f32 v[42:43], v[68:69], v[72:73]
	v_pk_mul_f32 v[44:45], v[70:71], v[88:89]
	v_pk_mul_f32 v[46:47], v[68:69], v[82:83]
	v_pk_mul_f32 v[48:49], v[70:71], v[90:91]
	v_pk_mul_f32 v[68:69], v[68:69], v[32:33]
	v_pk_mul_f32 v[70:71], v[70:71], v[86:87]
	v_mov_b32_e32 v120, v64
	v_mov_b32_e32 v121, v46
	v_mov_b32_e32 v122, v65
	v_mov_b32_e32 v123, v47
	v_mov_b32_e32 v124, v42
	v_mov_b32_e32 v125, v50
	v_mov_b32_e32 v126, v43
	v_mov_b32_e32 v127, v51
	v_mov_b32_e32 v128, v66
	v_mov_b32_e32 v129, v48
	v_mov_b32_e32 v130, v67
	v_mov_b32_e32 v131, v49
	v_mov_b32_e32 v132, v44
	v_mov_b32_e32 v133, v52
	v_mov_b32_e32 v134, v45
	v_mov_b32_e32 v135, v53
	ds_write_b128 v80, v[68:71] offset:1024
	v_cvt_f32_f16_e32 v51, v38
	v_cvt_f32_f16_sdwa v53, v38 dst_sel:DWORD dst_unused:UNUSED_PAD src0_sel:WORD_1
	v_cvt_f32_f16_e32 v50, v40
	v_cvt_f32_f16_sdwa v52, v40 dst_sel:DWORD dst_unused:UNUSED_PAD src0_sel:WORD_1
	v_cvt_f32_f16_e32 v63, v39
	v_cvt_f32_f16_sdwa v65, v39 dst_sel:DWORD dst_unused:UNUSED_PAD src0_sel:WORD_1
	v_cvt_f32_f16_e32 v62, v41
	v_cvt_f32_f16_sdwa v64, v41 dst_sel:DWORD dst_unused:UNUSED_PAD src0_sel:WORD_1
	v_mov_b32_e32 v42, v51
	v_mov_b32_e32 v43, v53
	v_mov_b32_e32 v44, v50
	v_mov_b32_e32 v45, v52
	v_mov_b32_e32 v38, v63
	v_mov_b32_e32 v39, v65
	v_pk_mul_f32 v[42:43], v[32:33], v[42:43]
	v_pk_mul_f32 v[46:47], v[32:33], v[44:45]
	v_mov_b32_e32 v32, v83
	v_pk_mul_f32 v[44:45], v[86:87], v[38:39]
	v_mov_b32_e32 v38, v62
	v_mov_b32_e32 v39, v64
	v_pk_fma_f32 v[40:41], v[82:83], v[50:51], 0 op_sel_hi:[0,1,0]
	v_pk_mul_f32 v[48:49], v[86:87], v[38:39]
	v_mov_b32_e32 v182, v42
	v_mov_b32_e32 v183, v43
	v_mov_b32_e32 v184, v44
	v_mov_b32_e32 v185, v45
	ds_write_b128 v80, v[46:49] offset:1536
	v_pk_fma_f32 v[32:33], v[32:33], v[52:53], v[40:41] op_sel_hi:[0,1,1]
	v_mov_b32_e32 v40, v73
	v_pk_fma_f32 v[44:45], v[72:73], v[50:51], 0 op_sel_hi:[0,1,0]
	v_pk_fma_f32 v[40:41], v[40:41], v[52:53], v[44:45] op_sel_hi:[0,1,1]
	v_pk_fma_f32 v[44:45], v[84:85], v[50:51], 0 op_sel_hi:[0,1,0]
	v_pk_fma_f32 v[44:45], v[84:85], v[52:53], v[44:45] op_sel:[1,0,0]
	v_mov_b32_e32 v38, v91
	v_pk_fma_f32 v[32:33], v[90:91], v[62:63], v[32:33] op_sel_hi:[0,1,1]
	v_mov_b32_e32 v42, v89
	v_pk_fma_f32 v[40:41], v[88:89], v[62:63], v[40:41] op_sel_hi:[0,1,1]
	v_pk_fma_f32 v[44:45], v[94:95], v[62:63], v[44:45] op_sel_hi:[0,1,1]
	v_pk_fma_f32 v[32:33], v[38:39], v[64:65], v[32:33] op_sel_hi:[0,1,1]
	v_pk_fma_f32 v[40:41], v[42:43], v[64:65], v[40:41] op_sel_hi:[0,1,1]
	v_pk_fma_f32 v[44:45], v[94:95], v[64:65], v[44:45] op_sel:[1,0,0]
	v_cvt_f32_f16_e32 v49, v34
	v_cvt_f32_f16_sdwa v51, v34 dst_sel:DWORD dst_unused:UNUSED_PAD src0_sel:WORD_1
	v_cvt_f32_f16_e32 v63, v35
	v_cvt_f32_f16_sdwa v65, v35 dst_sel:DWORD dst_unused:UNUSED_PAD src0_sel:WORD_1
	v_cvt_f32_f16_e32 v48, v36
	v_cvt_f32_f16_sdwa v50, v36 dst_sel:DWORD dst_unused:UNUSED_PAD src0_sel:WORD_1
	v_cvt_f32_f16_e32 v62, v37
	v_cvt_f32_f16_sdwa v64, v37 dst_sel:DWORD dst_unused:UNUSED_PAD src0_sel:WORD_1
	v_mov_b32_e32 v34, v49
	v_mov_b32_e32 v35, v51
	v_mov_b32_e32 v36, v63
	v_mov_b32_e32 v37, v65
	ds_write_b128 v80, v[34:37] offset:1792
	v_mov_b32_e32 v34, v48
	v_mov_b32_e32 v35, v50
	v_mov_b32_e32 v36, v62
	v_mov_b32_e32 v37, v64
	v_mov_b32_e32 v52, v75
	ds_write_b128 v80, v[34:37] offset:2048
	v_mov_b32_e32 v186, v34
	v_mov_b32_e32 v187, v35
	v_mov_b32_e32 v188, v36
	v_mov_b32_e32 v189, v37
	v_pk_fma_f32 v[34:35], v[74:75], v[48:49], 0 op_sel_hi:[0,1,0]
	v_pk_fma_f32 v[34:35], v[52:53], v[50:51], v[34:35] op_sel_hi:[0,1,1]
	v_mov_b32_e32 v66, v93
	v_pk_fma_f32 v[34:35], v[92:93], v[62:63], v[34:35] op_sel_hi:[0,1,1]
	v_pk_fma_f32 v[34:35], v[66:67], v[64:65], v[34:35] op_sel_hi:[0,1,1]
	v_mov_b32_dpp v38, v32 row_ror:8 row_mask:0xf bank_mask:0xf bound_ctrl:1
	v_mov_b32_dpp v39, v33 row_ror:8 row_mask:0xf bank_mask:0xf bound_ctrl:1
	v_mov_b32_dpp v42, v40 row_ror:8 row_mask:0xf bank_mask:0xf bound_ctrl:1
	v_mov_b32_dpp v43, v41 row_ror:8 row_mask:0xf bank_mask:0xf bound_ctrl:1
	v_mov_b32_dpp v46, v44 row_ror:8 row_mask:0xf bank_mask:0xf bound_ctrl:1
	v_mov_b32_dpp v47, v45 row_ror:8 row_mask:0xf bank_mask:0xf bound_ctrl:1
	v_mov_b32_dpp v36, v34 row_ror:8 row_mask:0xf bank_mask:0xf bound_ctrl:1
	v_mov_b32_dpp v37, v35 row_ror:8 row_mask:0xf bank_mask:0xf bound_ctrl:1
	v_pk_add_f32 v[32:33], v[32:33], v[38:39]
	v_pk_add_f32 v[40:41], v[40:41], v[42:43]
	v_pk_add_f32 v[44:45], v[44:45], v[46:47]
	v_pk_add_f32 v[34:35], v[34:35], v[36:37]
	v_mov_b32_dpp v38, v32 row_ror:4 row_mask:0xf bank_mask:0xf bound_ctrl:1
	v_mov_b32_dpp v39, v33 row_ror:4 row_mask:0xf bank_mask:0xf bound_ctrl:1
	v_mov_b32_dpp v42, v40 row_ror:4 row_mask:0xf bank_mask:0xf bound_ctrl:1
	v_mov_b32_dpp v43, v41 row_ror:4 row_mask:0xf bank_mask:0xf bound_ctrl:1
	v_mov_b32_dpp v46, v44 row_ror:4 row_mask:0xf bank_mask:0xf bound_ctrl:1
	v_mov_b32_dpp v47, v45 row_ror:4 row_mask:0xf bank_mask:0xf bound_ctrl:1
	v_mov_b32_dpp v36, v34 row_ror:4 row_mask:0xf bank_mask:0xf bound_ctrl:1
	v_mov_b32_dpp v37, v35 row_ror:4 row_mask:0xf bank_mask:0xf bound_ctrl:1
	v_pk_add_f32 v[32:33], v[32:33], v[38:39]
	v_pk_add_f32 v[40:41], v[40:41], v[42:43]
	v_pk_add_f32 v[44:45], v[44:45], v[46:47]
	v_pk_add_f32 v[34:35], v[34:35], v[36:37]
	v_mov_b32_dpp v38, v32 row_ror:2 row_mask:0xf bank_mask:0xf bound_ctrl:1
	v_mov_b32_dpp v39, v33 row_ror:2 row_mask:0xf bank_mask:0xf bound_ctrl:1
	v_mov_b32_dpp v42, v40 row_ror:2 row_mask:0xf bank_mask:0xf bound_ctrl:1
	v_mov_b32_dpp v43, v41 row_ror:2 row_mask:0xf bank_mask:0xf bound_ctrl:1
	v_mov_b32_dpp v46, v44 row_ror:2 row_mask:0xf bank_mask:0xf bound_ctrl:1
	v_mov_b32_dpp v47, v45 row_ror:2 row_mask:0xf bank_mask:0xf bound_ctrl:1
	v_mov_b32_dpp v36, v34 row_ror:2 row_mask:0xf bank_mask:0xf bound_ctrl:1
	v_mov_b32_dpp v37, v35 row_ror:2 row_mask:0xf bank_mask:0xf bound_ctrl:1
	v_pk_add_f32 v[32:33], v[32:33], v[38:39]
	v_pk_add_f32 v[40:41], v[40:41], v[42:43]
	v_pk_add_f32 v[44:45], v[44:45], v[46:47]
	v_pk_add_f32 v[34:35], v[34:35], v[36:37]
	v_mov_b32_dpp v38, v32 row_ror:1 row_mask:0xf bank_mask:0xf bound_ctrl:1
	v_mov_b32_dpp v39, v33 row_ror:1 row_mask:0xf bank_mask:0xf bound_ctrl:1
	v_mov_b32_dpp v42, v40 row_ror:1 row_mask:0xf bank_mask:0xf bound_ctrl:1
	v_mov_b32_dpp v43, v41 row_ror:1 row_mask:0xf bank_mask:0xf bound_ctrl:1
	v_mov_b32_dpp v46, v44 row_ror:1 row_mask:0xf bank_mask:0xf bound_ctrl:1
	v_mov_b32_dpp v47, v45 row_ror:1 row_mask:0xf bank_mask:0xf bound_ctrl:1
	v_mov_b32_dpp v36, v34 row_ror:1 row_mask:0xf bank_mask:0xf bound_ctrl:1
	v_mov_b32_dpp v37, v35 row_ror:1 row_mask:0xf bank_mask:0xf bound_ctrl:1
	s_and_saveexec_b64 s[20:21], s[0:1]
	s_cbranch_execz .LBB0_663
	v_pk_add_f32 v[38:39], v[32:33], v[38:39]
	v_pk_add_f32 v[32:33], v[40:41], v[42:43]
	s_mov_b32 s10, 0x3d800000
	v_pk_mul_f32 v[40:41], v[32:33], s[10:11] op_sel_hi:[1,0]
	v_pk_add_f32 v[32:33], v[44:45], v[46:47]
	v_pk_add_f32 v[34:35], v[34:35], v[36:37]
	v_pk_mul_f32 v[32:33], v[32:33], s[10:11] op_sel_hi:[1,0]
	v_pk_mul_f32 v[34:35], v[34:35], s[10:11] op_sel_hi:[1,0]
	ds_write_b128 v77, v[38:41] offset:36864
	ds_write_b128 v77, v[32:35] offset:36880
.LBB0_663:
	s_or_b64 exec, exec, s[20:21]
	s_add_u32 s20, s78, 0xf000000
	s_addc_u32 s21, s79, 0
	s_add_u32 s7, s20, s6
	s_addc_u32 s9, s21, 0
	s_add_u32 s22, s7, s8
	s_addc_u32 s23, s9, 0
	v_mov_b32_e32 v3, 0
	s_waitcnt vmcnt(11)
	v_cvt_f32_f16_sdwa v35, v61 dst_sel:DWORD dst_unused:UNUSED_PAD src0_sel:WORD_1
	v_cvt_f32_f16_e32 v34, v61
	v_lshl_add_u64 v[32:33], s[22:23], 0, v[2:3]
	s_mov_b64 s[22:23], 0x20000
	v_lshl_add_u64 v[38:39], v[28:29], 0, s[22:23]
	v_or_b32_e32 v28, v38, v55
	v_mov_b32_e32 v29, v39
	v_or_b32_e32 v38, v38, v54
	v_lshlrev_b64 v[30:31], 12, v[30:31]
	ds_write_b64 v1, v[34:35] offset:37632
	ds_read_b128 v[198:201], v216 offset:36864
	ds_read_b128 v[202:205], v216 offset:36880
	ds_read2_b32 v[206:207], v220 offset1:16
	s_waitcnt lgkmcnt(0)
	v_mul_f32_e32 v210, 0x41800000, v200
	v_mul_f32_e32 v211, 0x41800000, v202
	v_mul_f32_e32 v212, 0x41800000, v204
	v_fma_f32 v213, -v204, v199, v203
	v_fma_f32 v121, -v198, v120, v121
	v_fma_f32 v123, -v198, v122, v123
	ds_write_b128 v218, v[120:123]
	v_fma_f32 v124, -v210, v120, v124
	v_fma_f32 v125, -v211, v120, v125
	v_fma_f32 v125, -v212, v121, v125
	v_fma_f32 v126, -v210, v122, v126
	v_fma_f32 v127, -v211, v122, v127
	v_fma_f32 v127, -v212, v123, v127
	ds_write_b128 v218, v[124:127] offset:256
	v_fma_f32 v129, -v198, v128, v129
	v_fma_f32 v131, -v198, v130, v131
	ds_write_b128 v218, v[128:131] offset:512
	v_fma_f32 v132, -v210, v128, v132
	v_fma_f32 v133, -v211, v128, v133
	v_fma_f32 v133, -v212, v129, v133
	v_fma_f32 v134, -v210, v130, v134
	v_fma_f32 v135, -v211, v130, v135
	v_fma_f32 v135, -v212, v131, v135
	ds_write_b128 v218, v[132:135] offset:768
	v_fma_f32 v182, -v199, v186, v182
	v_fma_f32 v183, -v199, v187, v183
	v_fma_f32 v184, -v199, v188, v184
	v_fma_f32 v185, -v199, v189, v185
	ds_write_b128 v218, v[182:185] offset:1280
	v_mul_f32_e32 v208, v206, v201
	v_mul_f32_e32 v209, v206, v213
	v_fmac_f32_e32 v209, v207, v205
	ds_write_b128 v222, v[206:209]
	v_lshlrev_b64 v[34:35], 1, v[28:29]
	v_lshlrev_b64 v[44:45], 1, v[38:39]
	s_mov_b32 s7, 0x40000
	v_lshl_add_u64 v[52:53], v[32:33], 0, v[30:31]
	v_lshl_add_u64 v[28:29], s[70:71], 0, v[34:35]
	v_lshl_add_u64 v[30:31], s[12:13], 0, v[34:35]
	v_lshl_add_u64 v[32:33], s[14:15], 0, v[34:35]
	v_lshl_add_u64 v[36:37], s[16:17], 0, v[34:35]
	v_lshl_add_u64 v[40:41], s[18:19], 0, v[34:35]
	v_lshl_add_u64 v[38:39], s[70:71], 0, v[44:45]
	v_lshl_add_u64 v[42:43], s[12:13], 0, v[44:45]
	v_lshl_add_u64 v[46:47], s[14:15], 0, v[44:45]
	v_add_co_u32_e32 v48, vcc, s7, v56
	global_load_dwordx2 v[28:29], v[28:29], off
	s_nop 0
	global_load_dwordx2 v[30:31], v[30:31], off
	s_nop 0
	global_load_dwordx2 v[32:33], v[32:33], off
	s_nop 0
	global_load_dwordx2 v[34:35], v[36:37], off
	s_nop 0
	global_load_dwordx2 v[36:37], v[40:41], off
	s_nop 0
	global_load_dwordx2 v[40:41], v[38:39], off
	s_nop 0
	global_load_dwordx2 v[38:39], v[42:43], off
	s_nop 0
	global_load_dwordx2 v[42:43], v[46:47], off
	v_lshl_add_u64 v[46:47], s[16:17], 0, v[44:45]
	v_lshl_add_u64 v[44:45], s[18:19], 0, v[44:45]
	v_addc_co_u32_e32 v49, vcc, 0, v57, vcc
	global_load_dwordx2 v[46:47], v[46:47], off
	s_nop 0
	global_load_dwordx2 v[44:45], v[44:45], off
	v_or_b32_e32 v3, v60, v58
	global_load_dword v81, v[48:49], off
	v_lshlrev_b32_e32 v3, 6, v3
	v_add_u32_e32 v3, 0, v3
	v_bfe_u32 v177, v152, 4, 1
	v_sub_u32_e32 v176, 0, v177
	v_lshlrev_b32_e32 v178, 6, v177
	v_sub_u32_e32 v179, 64, v178
	v_bfe_u32 v177, v152, 1, 2
	v_add_u32_e32 v180, 0, v177
	v_and_b32_e32 v180, 3, v180
	v_lshlrev_b32_e32 v180, 4, v180
	v_add3_u32 v160, v3, v178, v180
	v_add3_u32 v164, v3, v179, v180
	v_add_u32_e32 v180, 1, v177
	v_and_b32_e32 v180, 3, v180
	v_lshlrev_b32_e32 v180, 4, v180
	v_add3_u32 v161, v3, v178, v180
	v_add3_u32 v165, v3, v179, v180
	v_add_u32_e32 v180, 2, v177
	v_and_b32_e32 v180, 3, v180
	v_lshlrev_b32_e32 v180, 4, v180
	v_add3_u32 v162, v3, v178, v180
	v_add3_u32 v166, v3, v179, v180
	v_add_u32_e32 v180, 3, v177
	v_and_b32_e32 v180, 3, v180
	v_lshlrev_b32_e32 v180, 4, v180
	v_add3_u32 v163, v3, v178, v180
	v_add3_u32 v167, v3, v179, v180
	v_add_u32_e32 v168, 0x11b00, v160
	v_add_u32_e32 v169, 0x11b00, v161
	v_add_u32_e32 v170, 0x11b00, v162
	v_add_u32_e32 v171, 0x11b00, v163
	v_add_u32_e32 v172, 0x11b00, v164
	v_add_u32_e32 v173, 0x11b00, v165
	v_add_u32_e32 v174, 0x11b00, v166
	v_add_u32_e32 v175, 0x11b00, v167
	ds_read_b128 v[120:123], v160 offset:39680
	ds_read_b128 v[124:127], v161 offset:39680
	ds_read_b128 v[128:131], v162 offset:39680
	ds_read_b128 v[132:135], v163 offset:39680
	ds_read_b128 v[136:139], v164 offset:39680
	ds_read_b128 v[140:143], v165 offset:39680
	ds_read_b128 v[144:147], v166 offset:39680
	ds_read_b128 v[148:151], v167 offset:39680
	s_movk_i32 s7, 0x7fff
	v_mov_b32_e32 v82, 1
	s_mov_b32 s9, 0xffff0000
	s_lshl_b32 s10, s2, 20
	s_and_b32 s10, s10, 0x4000000
	s_waitcnt lgkmcnt(0)
	v_pk_add_f32 v[120:121], v[120:121], v[124:125]
	v_pk_add_f32 v[122:123], v[122:123], v[126:127]
	v_pk_add_f32 v[128:129], v[128:129], v[132:133]
	v_pk_add_f32 v[130:131], v[130:131], v[134:135]
	v_pk_add_f32 v[120:121], v[120:121], v[128:129]
	v_pk_add_f32 v[122:123], v[122:123], v[130:131]
	v_pk_add_f32 v[120:121], v[120:121], v[122:123]
	v_add_f32_e32 v120, v120, v121
	v_pk_add_f32 v[136:137], v[136:137], v[140:141]
	v_pk_add_f32 v[138:139], v[138:139], v[142:143]
	v_pk_add_f32 v[144:145], v[144:145], v[148:149]
	v_pk_add_f32 v[146:147], v[146:147], v[150:151]
	v_pk_add_f32 v[136:137], v[136:137], v[144:145]
	v_pk_add_f32 v[138:139], v[138:139], v[146:147]
	v_pk_add_f32 v[136:137], v[136:137], v[138:139]
	v_add_f32_e32 v136, v136, v137
	v_bfi_b32 v49, v176, v136, v120
	v_bfi_b32 v48, v176, v120, v136
	v_and_b32_sdwa v50, v49, v82 dst_sel:DWORD dst_unused:UNUSED_PAD src0_sel:WORD_1 src1_sel:DWORD
	v_and_b32_sdwa v51, v48, v82 dst_sel:DWORD dst_unused:UNUSED_PAD src0_sel:WORD_1 src1_sel:DWORD
	v_add3_u32 v49, v49, v50, s7
	v_add3_u32 v48, v48, v51, s7
	v_lshrrev_b32_e32 v49, 16, v49
	v_and_or_b32 v48, v48, s9, v49
	global_store_dword v[52:53], v48, off
	v_lshlrev_b64 v[48:49], 12, v[4:5]
	v_lshl_add_u64 v[48:49], s[10:11], 0, v[48:49]
	s_lshl_b32 s10, s25, 5
	v_and_b32_e32 v50, 7, v153
	s_and_b32 s14, s10, 0x780
	v_lshlrev_b32_e32 v52, 2, v50
	v_lshlrev_b64 v[50:51], 11, v[4:5]
	v_or_b32_e32 v48, s14, v48
	s_and_b32 s15, s24, 0x60
	v_or_b32_e32 v50, s14, v50
	v_or3_b32 v48, v48, s15, v52
	v_or3_b32 v50, v50, s15, v52
	v_lshlrev_b64 v[52:53], 11, v[26:27]
	v_lshl_add_u64 v[48:49], s[78:79], 0, v[48:49]
	s_mov_b64 s[12:13], 0xf040000
	s_lshl_b32 s10, s2, 19
	v_lshl_or_b32 v52, v55, 1, v52
	v_lshl_add_u64 v[48:49], v[48:49], 0, s[12:13]
	s_and_b32 s10, s10, 0x2000000
	v_lshl_add_u64 v[50:51], s[70:71], 0, v[50:51]
	v_lshl_add_u64 v[26:27], s[70:71], 0, v[52:53]
	v_lshl_add_u64 v[52:53], s[78:79], 0, v[52:53]
	s_mov_b32 s12, 0x3d800000
	s_mov_b64 s[14:15], 0x40000
	s_mov_b32 s13, s11
	s_barrier
	s_branch .LBB0_665
